# EpiResid epilogues (3 sites): second batch of residual loads issued with the first into spare regs, counted waits re-derived
# speedup vs baseline: 1.0125x; 1.0015x over previous
.LBB0_475:
	v_lshl_add_u32 v122, s33, 8, v182
	s_lshl_b32 s6, s18, 8
	v_lshl_add_u32 v48, v122, 10, s6
	v_or_b32_e32 v48, v48, v184
	v_lshl_add_u64 v[194:195], v[48:49], 1, s[16:17]
	global_load_dwordx4 v[186:189], v[194:195], off
	s_lshl_b32 s6, s18, 16
	s_or_b32 s6, s6, s65
	v_add_u32_e32 v168, s6, v122
	v_or_b32_e32 v122, 0x80, v48
	v_mov_b32_e32 v123, v49
	v_lshl_add_u64 v[196:197], v[122:123], 1, s[16:17]
	global_load_dwordx4 v[190:193], v[196:197], off
	v_add_u32_e32 v122, 0x4000, v48
	v_lshl_add_u64 v[180:181], v[122:123], 1, s[16:17]
	v_add_u32_e32 v122, 0x4080, v48
	v_lshl_add_u64 v[178:179], v[122:123], 1, s[16:17]
	v_add_u32_e32 v122, 0x8000, v48
	v_lshl_add_u64 v[176:177], v[122:123], 1, s[16:17]
	v_add_u32_e32 v122, 0x8080, v48
	v_lshl_add_u64 v[174:175], v[122:123], 1, s[16:17]
	v_add_u32_e32 v122, 0xc000, v48
	v_add_u32_e32 v130, 0xc080, v48
	v_mov_b32_e32 v131, v49
	v_lshl_add_u64 v[172:173], v[122:123], 1, s[16:17]
	v_lshl_add_u64 v[170:171], v[130:131], 1, s[16:17]
	global_load_dwordx4 v[150:153], v[180:181], off
	global_load_dwordx4 v[146:149], v[178:179], off
	global_load_dwordx4 v[142:145], v[176:177], off
	global_load_dwordx4 v[138:141], v[174:175], off
	global_load_dwordx4 v[122:125], v[172:173], off
	global_load_dwordx4 v[130:133], v[170:171], off
	v_mov_b32_e32 v245, v49
	v_add_u32_e32 v244, 0x20000, v48
	v_lshl_add_u64 v[156:157], v[244:245], 1, s[16:17]
	global_load_dwordx4 v[212:215], v[156:157], off
	v_add_u32_e32 v244, 0x20080, v48
	v_lshl_add_u64 v[158:159], v[244:245], 1, s[16:17]
	global_load_dwordx4 v[216:219], v[158:159], off
	v_add_u32_e32 v244, 0x24000, v48
	v_lshl_add_u64 v[160:161], v[244:245], 1, s[16:17]
	global_load_dwordx4 v[220:223], v[160:161], off
	v_add_u32_e32 v244, 0x24080, v48
	v_lshl_add_u64 v[162:163], v[244:245], 1, s[16:17]
	global_load_dwordx4 v[224:227], v[162:163], off
	v_add_u32_e32 v244, 0x28000, v48
	v_lshl_add_u64 v[164:165], v[244:245], 1, s[16:17]
	global_load_dwordx4 v[228:231], v[164:165], off
	v_add_u32_e32 v244, 0x28080, v48
	v_lshl_add_u64 v[166:167], v[244:245], 1, s[16:17]
	global_load_dwordx4 v[232:235], v[166:167], off
	v_add_u32_e32 v244, 0x2c000, v48
	v_lshl_add_u64 v[248:249], v[244:245], 1, s[16:17]
	global_load_dwordx4 v[236:239], v[248:249], off
	v_add_u32_e32 v244, 0x2c080, v48
	v_lshl_add_u64 v[250:251], v[244:245], 1, s[16:17]
	global_load_dwordx4 v[240:243], v[250:251], off
	s_waitcnt vmcnt(8)
	v_lshlrev_b32_e32 v198, 16, v186
	v_and_b32_e32 v199, 0xffff0000, v186
	v_lshlrev_b32_e32 v186, 16, v187
	v_and_b32_e32 v187, 0xffff0000, v187
	v_pk_fma_f32 v[136:137], v[136:137], 0.5, v[186:187] op_sel_hi:[1,0,1]
	v_pk_fma_f32 v[134:135], v[134:135], 0.5, v[198:199] op_sel_hi:[1,0,1]
	v_lshlrev_b32_e32 v186, 16, v188
	v_and_b32_e32 v187, 0xffff0000, v188
	v_lshlrev_b32_e32 v188, 16, v189
	v_and_b32_e32 v189, 0xffff0000, v189
	v_pk_fma_f32 v[188:189], v[128:129], 0.5, v[188:189] op_sel_hi:[1,0,1]
	v_pk_fma_f32 v[186:187], v[126:127], 0.5, v[186:187] op_sel_hi:[1,0,1]
	v_cvt_pk_bf16_f32 v126, v134, v135
	v_cvt_pk_bf16_f32 v127, v136, v137
	v_cvt_pk_bf16_f32 v128, v186, v187
	v_cvt_pk_bf16_f32 v129, v188, v189
	global_store_dwordx4 v[194:195], v[126:129], off
	s_nop 1
	v_mul_f32_e32 v126, v135, v135
	v_mul_f32_e32 v127, v137, v137
	v_fmac_f32_e32 v126, v134, v134
	v_fmac_f32_e32 v127, v136, v136
	v_add_f32_e32 v126, v126, v127
	v_mul_f32_e32 v127, v187, v187
	v_mul_f32_e32 v128, v189, v189
	v_fmac_f32_e32 v127, v186, v186
	v_fmac_f32_e32 v128, v188, v188
	v_add_f32_e32 v127, v127, v128
	v_add_f32_e32 v134, v126, v127
	v_lshlrev_b32_e32 v126, 16, v190
	v_and_b32_e32 v127, 0xffff0000, v190
	v_lshlrev_b32_e32 v128, 16, v191
	v_and_b32_e32 v129, 0xffff0000, v191
	v_pk_fma_f32 v[120:121], v[120:121], 0.5, v[128:129] op_sel_hi:[1,0,1]
	v_pk_fma_f32 v[118:119], v[118:119], 0.5, v[126:127] op_sel_hi:[1,0,1]
	v_lshlrev_b32_e32 v126, 16, v192
	v_and_b32_e32 v127, 0xffff0000, v192
	v_lshlrev_b32_e32 v128, 16, v193
	v_and_b32_e32 v129, 0xffff0000, v193
	v_pk_fma_f32 v[128:129], v[116:117], 0.5, v[128:129] op_sel_hi:[1,0,1]
	v_pk_fma_f32 v[126:127], v[114:115], 0.5, v[126:127] op_sel_hi:[1,0,1]
	v_cvt_pk_bf16_f32 v114, v118, v119
	v_cvt_pk_bf16_f32 v115, v120, v121
	v_cvt_pk_bf16_f32 v116, v126, v127
	v_cvt_pk_bf16_f32 v117, v128, v129
	global_store_dwordx4 v[196:197], v[114:117], off
	s_nop 1
	v_mul_f32_e32 v114, v119, v119
	v_mul_f32_e32 v115, v121, v121
	v_fmac_f32_e32 v114, v118, v118
	v_fmac_f32_e32 v115, v120, v120
	v_add_f32_e32 v114, v114, v115
	v_mul_f32_e32 v115, v127, v127
	v_mul_f32_e32 v116, v129, v129
	v_fmac_f32_e32 v115, v126, v126
	v_fmac_f32_e32 v116, v128, v128
	v_add_f32_e32 v115, v115, v116
	v_add_f32_e32 v114, v114, v115
	v_and_b32_e32 v116, 64, v205
	v_add_f32_e32 v115, v134, v114
	v_xor_b32_e32 v114, 16, v205
	v_add_u32_e32 v116, 64, v116
	v_cmp_lt_i32_e32 vcc, v114, v116
	s_nop 1
	v_cndmask_b32_e32 v114, v205, v114, vcc
	v_lshlrev_b32_e32 v114, 2, v114
	s_waitcnt lgkmcnt(0)
	v_mov_b32_e32 v116, v115
	s_nop 1
	v_permlane16_swap_b32_e32 v115, v116
	v_add_f32_e32 v115, v115, v116
	v_mov_b32_e32 v116, v115
	s_nop 1
	v_permlane32_swap_b32_e32 v115, v116
	s_and_saveexec_b64 s[50:51], s[38:39]
	s_cbranch_execz .LBB0_477
	v_mov_b32_e32 v169, v49
	v_lshl_add_u64 v[118:119], v[168:169], 2, s[22:23]
	v_add_f32_e32 v115, v115, v116
	global_store_dword v[118:119], v115, off

.LBB0_483:
	s_or_b64 exec, exec, s[50:51]
	v_add_u32_e32 v66, 0x20000, v48
	v_mov_b32_e32 v67, v49
	v_lshl_add_u64 v[112:113], v[66:67], 1, s[16:17]
	v_add_u32_e32 v66, 0x20080, v48
	v_lshl_add_u64 v[106:107], v[66:67], 1, s[16:17]
	v_add_u32_e32 v66, 0x24000, v48
	v_lshl_add_u64 v[104:105], v[66:67], 1, s[16:17]
	v_add_u32_e32 v66, 0x24080, v48
	v_lshl_add_u64 v[102:103], v[66:67], 1, s[16:17]
	v_add_u32_e32 v66, 0x28000, v48
	v_lshl_add_u64 v[100:101], v[66:67], 1, s[16:17]
	v_add_u32_e32 v66, 0x28080, v48
	v_lshl_add_u64 v[98:99], v[66:67], 1, s[16:17]
	v_add_u32_e32 v66, 0x2c000, v48
	v_add_u32_e32 v48, 0x2c080, v48
	v_lshl_add_u64 v[96:97], v[66:67], 1, s[16:17]
	v_lshl_add_u64 v[94:95], v[48:49], 1, s[16:17]
	s_waitcnt vmcnt(4)
	v_lshlrev_b32_e32 v116, 16, v212
	v_and_b32_e32 v117, 0xffff0000, v212
	v_lshlrev_b32_e32 v108, 16, v213
	v_and_b32_e32 v109, 0xffff0000, v213
	v_pk_fma_f32 v[64:65], v[64:65], 0.5, v[108:109] op_sel_hi:[1,0,1]
	v_pk_fma_f32 v[62:63], v[62:63], 0.5, v[116:117] op_sel_hi:[1,0,1]
	v_lshlrev_b32_e32 v108, 16, v214
	v_and_b32_e32 v109, 0xffff0000, v214
	v_lshlrev_b32_e32 v110, 16, v215
	v_and_b32_e32 v111, 0xffff0000, v215
	v_pk_fma_f32 v[110:111], v[60:61], 0.5, v[110:111] op_sel_hi:[1,0,1]
	v_pk_fma_f32 v[108:109], v[58:59], 0.5, v[108:109] op_sel_hi:[1,0,1]
	v_cvt_pk_bf16_f32 v58, v62, v63
	v_cvt_pk_bf16_f32 v59, v64, v65
	v_cvt_pk_bf16_f32 v60, v108, v109
	v_cvt_pk_bf16_f32 v61, v110, v111
	global_store_dwordx4 v[112:113], v[58:61], off
	s_nop 1
	v_mul_f32_e32 v48, v63, v63
	v_mul_f32_e32 v58, v65, v65
	v_fmac_f32_e32 v48, v62, v62
	v_fmac_f32_e32 v58, v64, v64
	v_add_f32_e32 v48, v48, v58
	v_mul_f32_e32 v58, v109, v109
	v_mul_f32_e32 v59, v111, v111
	v_fmac_f32_e32 v58, v108, v108
	v_fmac_f32_e32 v59, v110, v110
	v_add_f32_e32 v58, v58, v59
	v_add_f32_e32 v48, v48, v58
	v_lshlrev_b32_e32 v58, 16, v216
	v_and_b32_e32 v59, 0xffff0000, v216
	v_lshlrev_b32_e32 v60, 16, v217
	v_and_b32_e32 v61, 0xffff0000, v217
	v_pk_fma_f32 v[56:57], v[56:57], 0.5, v[60:61] op_sel_hi:[1,0,1]
	v_pk_fma_f32 v[54:55], v[54:55], 0.5, v[58:59] op_sel_hi:[1,0,1]
	v_lshlrev_b32_e32 v58, 16, v218
	v_and_b32_e32 v59, 0xffff0000, v218
	v_lshlrev_b32_e32 v60, 16, v219
	v_and_b32_e32 v61, 0xffff0000, v219
	v_pk_fma_f32 v[60:61], v[52:53], 0.5, v[60:61] op_sel_hi:[1,0,1]
	v_pk_fma_f32 v[58:59], v[50:51], 0.5, v[58:59] op_sel_hi:[1,0,1]
	v_cvt_pk_bf16_f32 v50, v54, v55
	v_cvt_pk_bf16_f32 v51, v56, v57
	v_cvt_pk_bf16_f32 v52, v58, v59
	v_cvt_pk_bf16_f32 v53, v60, v61
	global_store_dwordx4 v[106:107], v[50:53], off
	s_nop 1
	v_mul_f32_e32 v50, v55, v55
	v_mul_f32_e32 v51, v57, v57
	v_fmac_f32_e32 v50, v54, v54
	v_fmac_f32_e32 v51, v56, v56
	v_add_f32_e32 v50, v50, v51
	v_mul_f32_e32 v51, v59, v59
	v_mul_f32_e32 v52, v61, v61
	v_fmac_f32_e32 v51, v58, v58
	v_fmac_f32_e32 v52, v60, v60
	v_add_f32_e32 v51, v51, v52
	v_add_f32_e32 v50, v50, v51
	v_add_f32_e32 v48, v48, v50
	ds_bpermute_b32 v50, v114, v48
	s_waitcnt lgkmcnt(0)
	v_add_f32_e32 v50, v48, v50
	v_mov_b32_e32 v51, v50
	s_nop 1
	v_permlane32_swap_b32_e32 v50, v51
	s_and_saveexec_b64 s[50:51], s[38:39]
	s_cbranch_execz .LBB0_485
	v_add_u32_e32 v48, 0x80, v168
	v_lshl_add_u64 v[52:53], v[48:49], 2, s[22:23]
	v_add_f32_e32 v48, v50, v51
	global_store_dword v[52:53], v48, off
.LBB0_485:
	s_or_b64 exec, exec, s[50:51]
	v_lshlrev_b32_e32 v50, 16, v220
	v_and_b32_e32 v51, 0xffff0000, v220
	v_lshlrev_b32_e32 v52, 16, v221
	v_and_b32_e32 v53, 0xffff0000, v221
	v_pk_fma_f32 v[46:47], v[46:47], 0.5, v[52:53] op_sel_hi:[1,0,1]
	v_pk_fma_f32 v[44:45], v[44:45], 0.5, v[50:51] op_sel_hi:[1,0,1]
	v_lshlrev_b32_e32 v50, 16, v222
	v_and_b32_e32 v51, 0xffff0000, v222
	v_lshlrev_b32_e32 v52, 16, v223
	v_and_b32_e32 v53, 0xffff0000, v223
	v_pk_fma_f32 v[52:53], v[42:43], 0.5, v[52:53] op_sel_hi:[1,0,1]
	v_pk_fma_f32 v[50:51], v[40:41], 0.5, v[50:51] op_sel_hi:[1,0,1]
	v_cvt_pk_bf16_f32 v40, v44, v45
	v_cvt_pk_bf16_f32 v41, v46, v47
	v_cvt_pk_bf16_f32 v42, v50, v51
	v_cvt_pk_bf16_f32 v43, v52, v53
	global_store_dwordx4 v[104:105], v[40:43], off
	s_nop 1
	v_mul_f32_e32 v40, v45, v45
	v_mul_f32_e32 v41, v47, v47
	v_fmac_f32_e32 v40, v44, v44
	v_fmac_f32_e32 v41, v46, v46
	v_add_f32_e32 v40, v40, v41
	v_mul_f32_e32 v41, v51, v51
	v_mul_f32_e32 v42, v53, v53
	v_fmac_f32_e32 v41, v50, v50
	v_fmac_f32_e32 v42, v52, v52
	v_add_f32_e32 v41, v41, v42
	v_add_f32_e32 v44, v40, v41
	v_lshlrev_b32_e32 v40, 16, v224
	v_and_b32_e32 v41, 0xffff0000, v224
	v_lshlrev_b32_e32 v42, 16, v225
	v_and_b32_e32 v43, 0xffff0000, v225
	v_pk_fma_f32 v[38:39], v[38:39], 0.5, v[42:43] op_sel_hi:[1,0,1]
	v_pk_fma_f32 v[36:37], v[36:37], 0.5, v[40:41] op_sel_hi:[1,0,1]
	v_lshlrev_b32_e32 v40, 16, v226
	v_and_b32_e32 v41, 0xffff0000, v226
	v_lshlrev_b32_e32 v42, 16, v227
	v_and_b32_e32 v43, 0xffff0000, v227
	v_pk_fma_f32 v[42:43], v[34:35], 0.5, v[42:43] op_sel_hi:[1,0,1]
	v_pk_fma_f32 v[34:35], v[32:33], 0.5, v[40:41] op_sel_hi:[1,0,1]
	v_mul_f32_e32 v33, v37, v37
	v_cvt_pk_bf16_f32 v32, v36, v37
	v_fmac_f32_e32 v33, v36, v36
	v_mul_f32_e32 v36, v39, v39
	v_fmac_f32_e32 v36, v38, v38
	v_add_f32_e32 v33, v33, v36
	v_mul_f32_e32 v36, v35, v35
	v_mul_f32_e32 v37, v43, v43
	v_fmac_f32_e32 v36, v34, v34
	v_fmac_f32_e32 v37, v42, v42
	v_add_f32_e32 v36, v36, v37
	v_add_f32_e32 v33, v33, v36
	v_add_f32_e32 v36, v44, v33
	ds_bpermute_b32 v37, v114, v36
	v_cvt_pk_bf16_f32 v33, v38, v39
	v_cvt_pk_bf16_f32 v34, v34, v35
	v_cvt_pk_bf16_f32 v35, v42, v43
	global_store_dwordx4 v[102:103], v[32:35], off
	s_nop 1
	s_waitcnt lgkmcnt(0)
	v_add_f32_e32 v32, v36, v37
	v_mov_b32_e32 v33, v32
	s_nop 1
	v_permlane32_swap_b32_e32 v32, v33
	s_and_saveexec_b64 s[50:51], s[38:39]
	s_cbranch_execz .LBB0_487
	v_add_u32_e32 v48, 0x90, v168
	v_lshl_add_u64 v[34:35], v[48:49], 2, s[22:23]
	v_add_f32_e32 v32, v32, v33
	global_store_dword v[34:35], v32, off
.LBB0_487:
	s_or_b64 exec, exec, s[50:51]
	v_lshlrev_b32_e32 v32, 16, v228
	v_and_b32_e32 v33, 0xffff0000, v228
	v_lshlrev_b32_e32 v34, 16, v229
	v_and_b32_e32 v35, 0xffff0000, v229
	v_pk_fma_f32 v[30:31], v[30:31], 0.5, v[34:35] op_sel_hi:[1,0,1]
	v_pk_fma_f32 v[28:29], v[28:29], 0.5, v[32:33] op_sel_hi:[1,0,1]
	v_lshlrev_b32_e32 v32, 16, v230
	v_and_b32_e32 v33, 0xffff0000, v230
	v_lshlrev_b32_e32 v34, 16, v231
	v_and_b32_e32 v35, 0xffff0000, v231
	v_pk_fma_f32 v[34:35], v[26:27], 0.5, v[34:35] op_sel_hi:[1,0,1]
	v_pk_fma_f32 v[32:33], v[24:25], 0.5, v[32:33] op_sel_hi:[1,0,1]
	v_cvt_pk_bf16_f32 v24, v28, v29
	v_cvt_pk_bf16_f32 v25, v30, v31
	v_cvt_pk_bf16_f32 v26, v32, v33
	v_cvt_pk_bf16_f32 v27, v34, v35
	global_store_dwordx4 v[100:101], v[24:27], off
	s_nop 1
	v_mul_f32_e32 v24, v29, v29
	v_mul_f32_e32 v25, v31, v31
	v_fmac_f32_e32 v24, v28, v28
	v_fmac_f32_e32 v25, v30, v30
	v_add_f32_e32 v24, v24, v25
	v_mul_f32_e32 v25, v33, v33
	v_mul_f32_e32 v26, v35, v35
	v_fmac_f32_e32 v25, v32, v32
	v_fmac_f32_e32 v26, v34, v34
	v_add_f32_e32 v25, v25, v26
	v_add_f32_e32 v28, v24, v25
	v_lshlrev_b32_e32 v24, 16, v232
	v_and_b32_e32 v25, 0xffff0000, v232
	v_lshlrev_b32_e32 v26, 16, v233
	v_and_b32_e32 v27, 0xffff0000, v233
	v_pk_fma_f32 v[22:23], v[22:23], 0.5, v[26:27] op_sel_hi:[1,0,1]
	v_pk_fma_f32 v[20:21], v[20:21], 0.5, v[24:25] op_sel_hi:[1,0,1]
	v_lshlrev_b32_e32 v24, 16, v234
	v_and_b32_e32 v25, 0xffff0000, v234
	v_lshlrev_b32_e32 v26, 16, v235
	v_and_b32_e32 v27, 0xffff0000, v235
	v_pk_fma_f32 v[26:27], v[18:19], 0.5, v[26:27] op_sel_hi:[1,0,1]
	v_pk_fma_f32 v[18:19], v[16:17], 0.5, v[24:25] op_sel_hi:[1,0,1]
	v_mul_f32_e32 v17, v21, v21
	v_cvt_pk_bf16_f32 v16, v20, v21
	v_fmac_f32_e32 v17, v20, v20
	v_mul_f32_e32 v20, v23, v23
	v_fmac_f32_e32 v20, v22, v22
	v_add_f32_e32 v17, v17, v20
	v_mul_f32_e32 v20, v19, v19
	v_mul_f32_e32 v21, v27, v27
	v_fmac_f32_e32 v20, v18, v18
	v_fmac_f32_e32 v21, v26, v26
	v_add_f32_e32 v20, v20, v21
	v_add_f32_e32 v17, v17, v20
	v_add_f32_e32 v20, v28, v17
	ds_bpermute_b32 v21, v114, v20
	v_cvt_pk_bf16_f32 v17, v22, v23
	v_cvt_pk_bf16_f32 v18, v18, v19
	v_cvt_pk_bf16_f32 v19, v26, v27
	global_store_dwordx4 v[98:99], v[16:19], off
	s_nop 1
	s_waitcnt lgkmcnt(0)
	v_add_f32_e32 v16, v20, v21
	v_mov_b32_e32 v17, v16
	s_nop 1
	v_permlane32_swap_b32_e32 v16, v17
	s_and_saveexec_b64 s[50:51], s[38:39]
	s_cbranch_execz .LBB0_489
	v_add_u32_e32 v48, 0xa0, v168
	v_lshl_add_u64 v[18:19], v[48:49], 2, s[22:23]
	v_add_f32_e32 v16, v16, v17
	global_store_dword v[18:19], v16, off
.LBB0_489:
	s_or_b64 exec, exec, s[50:51]
	v_lshlrev_b32_e32 v16, 16, v236
	v_and_b32_e32 v17, 0xffff0000, v236
	v_lshlrev_b32_e32 v18, 16, v237
	v_and_b32_e32 v19, 0xffff0000, v237
	v_pk_fma_f32 v[14:15], v[14:15], 0.5, v[18:19] op_sel_hi:[1,0,1]
	v_pk_fma_f32 v[12:13], v[12:13], 0.5, v[16:17] op_sel_hi:[1,0,1]
	v_lshlrev_b32_e32 v16, 16, v238
	v_and_b32_e32 v17, 0xffff0000, v238
	v_lshlrev_b32_e32 v18, 16, v239
	v_and_b32_e32 v19, 0xffff0000, v239
	v_pk_fma_f32 v[18:19], v[10:11], 0.5, v[18:19] op_sel_hi:[1,0,1]
	v_pk_fma_f32 v[16:17], v[8:9], 0.5, v[16:17] op_sel_hi:[1,0,1]
	v_cvt_pk_bf16_f32 v8, v12, v13
	v_cvt_pk_bf16_f32 v9, v14, v15
	v_cvt_pk_bf16_f32 v10, v16, v17
	v_cvt_pk_bf16_f32 v11, v18, v19
	global_store_dwordx4 v[96:97], v[8:11], off
	s_nop 1
	v_mul_f32_e32 v8, v13, v13
	v_mul_f32_e32 v9, v15, v15
	v_fmac_f32_e32 v8, v12, v12
	v_fmac_f32_e32 v9, v14, v14
	v_add_f32_e32 v8, v8, v9
	v_mul_f32_e32 v9, v17, v17
	v_mul_f32_e32 v10, v19, v19
	v_fmac_f32_e32 v9, v16, v16
	v_fmac_f32_e32 v10, v18, v18
	v_add_f32_e32 v9, v9, v10
	v_add_f32_e32 v12, v8, v9
	v_lshlrev_b32_e32 v8, 16, v240
	v_and_b32_e32 v9, 0xffff0000, v240
	v_lshlrev_b32_e32 v10, 16, v241
	v_and_b32_e32 v11, 0xffff0000, v241
	v_pk_fma_f32 v[6:7], v[6:7], 0.5, v[10:11] op_sel_hi:[1,0,1]
	v_pk_fma_f32 v[4:5], v[4:5], 0.5, v[8:9] op_sel_hi:[1,0,1]
	v_lshlrev_b32_e32 v8, 16, v242
	v_and_b32_e32 v9, 0xffff0000, v242
	v_lshlrev_b32_e32 v10, 16, v243
	v_and_b32_e32 v11, 0xffff0000, v243
	v_pk_fma_f32 v[10:11], v[2:3], 0.5, v[10:11] op_sel_hi:[1,0,1]
	v_pk_fma_f32 v[2:3], v[0:1], 0.5, v[8:9] op_sel_hi:[1,0,1]
	v_mul_f32_e32 v1, v5, v5
	v_cvt_pk_bf16_f32 v0, v4, v5
	v_fmac_f32_e32 v1, v4, v4
	v_mul_f32_e32 v4, v7, v7
	v_fmac_f32_e32 v4, v6, v6
	v_add_f32_e32 v1, v1, v4
	v_mul_f32_e32 v4, v3, v3
	v_mul_f32_e32 v5, v11, v11
	v_fmac_f32_e32 v4, v2, v2
	v_fmac_f32_e32 v5, v10, v10
	v_add_f32_e32 v4, v4, v5
	v_add_f32_e32 v1, v1, v4
	v_add_f32_e32 v4, v12, v1
	ds_bpermute_b32 v5, v114, v4
	v_cvt_pk_bf16_f32 v1, v6, v7
	v_cvt_pk_bf16_f32 v2, v2, v3
	v_cvt_pk_bf16_f32 v3, v10, v11
	global_store_dwordx4 v[94:95], v[0:3], off
	s_nop 1
	s_waitcnt lgkmcnt(0)
	v_add_f32_e32 v0, v4, v5
	v_mov_b32_e32 v1, v0
	s_nop 1
	v_permlane32_swap_b32_e32 v0, v1
	s_and_saveexec_b64 s[50:51], s[38:39]
	s_cbranch_execz .LBB0_491
	v_add_u32_e32 v48, 0xb0, v168
	v_lshl_add_u64 v[2:3], v[48:49], 2, s[22:23]
	v_add_f32_e32 v0, v0, v1
	global_store_dword v[2:3], v0, off

.LBB0_1304:
	v_lshl_add_u32 v122, s54, 8, v182
	s_lshl_b32 s6, s52, 8
	v_lshl_add_u32 v48, v122, 10, s6
	v_or_b32_e32 v48, v48, v184
	v_lshl_add_u64 v[194:195], v[48:49], 1, s[16:17]
	global_load_dwordx4 v[186:189], v[194:195], off
	s_lshl_b32 s6, s52, 16
	s_or_b32 s6, s6, s67
	v_add_u32_e32 v168, s6, v122
	v_or_b32_e32 v122, 0x80, v48
	v_mov_b32_e32 v123, v49
	v_lshl_add_u64 v[196:197], v[122:123], 1, s[16:17]
	global_load_dwordx4 v[190:193], v[196:197], off
	v_add_u32_e32 v122, 0x4000, v48
	v_lshl_add_u64 v[180:181], v[122:123], 1, s[16:17]
	v_add_u32_e32 v122, 0x4080, v48
	v_lshl_add_u64 v[178:179], v[122:123], 1, s[16:17]
	v_add_u32_e32 v122, 0x8000, v48
	v_lshl_add_u64 v[176:177], v[122:123], 1, s[16:17]
	v_add_u32_e32 v122, 0x8080, v48
	v_lshl_add_u64 v[174:175], v[122:123], 1, s[16:17]
	v_add_u32_e32 v122, 0xc000, v48
	v_add_u32_e32 v130, 0xc080, v48
	v_mov_b32_e32 v131, v49
	v_lshl_add_u64 v[172:173], v[122:123], 1, s[16:17]
	v_lshl_add_u64 v[170:171], v[130:131], 1, s[16:17]
	global_load_dwordx4 v[150:153], v[180:181], off
	global_load_dwordx4 v[146:149], v[178:179], off
	global_load_dwordx4 v[142:145], v[176:177], off
	global_load_dwordx4 v[138:141], v[174:175], off
	global_load_dwordx4 v[122:125], v[172:173], off
	global_load_dwordx4 v[130:133], v[170:171], off
	v_mov_b32_e32 v245, v49
	v_add_u32_e32 v244, 0x20000, v48
	v_lshl_add_u64 v[156:157], v[244:245], 1, s[16:17]
	global_load_dwordx4 v[212:215], v[156:157], off
	v_add_u32_e32 v244, 0x20080, v48
	v_lshl_add_u64 v[158:159], v[244:245], 1, s[16:17]
	global_load_dwordx4 v[216:219], v[158:159], off
	v_add_u32_e32 v244, 0x24000, v48
	v_lshl_add_u64 v[160:161], v[244:245], 1, s[16:17]
	global_load_dwordx4 v[220:223], v[160:161], off
	v_add_u32_e32 v244, 0x24080, v48
	v_lshl_add_u64 v[162:163], v[244:245], 1, s[16:17]
	global_load_dwordx4 v[224:227], v[162:163], off
	v_add_u32_e32 v244, 0x28000, v48
	v_lshl_add_u64 v[164:165], v[244:245], 1, s[16:17]
	global_load_dwordx4 v[228:231], v[164:165], off
	v_add_u32_e32 v244, 0x28080, v48
	v_lshl_add_u64 v[166:167], v[244:245], 1, s[16:17]
	global_load_dwordx4 v[232:235], v[166:167], off
	v_add_u32_e32 v244, 0x2c000, v48
	v_lshl_add_u64 v[248:249], v[244:245], 1, s[16:17]
	global_load_dwordx4 v[236:239], v[248:249], off
	v_add_u32_e32 v244, 0x2c080, v48
	v_lshl_add_u64 v[250:251], v[244:245], 1, s[16:17]
	global_load_dwordx4 v[240:243], v[250:251], off
	s_waitcnt vmcnt(8)
	v_lshlrev_b32_e32 v198, 16, v186
	v_and_b32_e32 v199, 0xffff0000, v186
	v_lshlrev_b32_e32 v186, 16, v187
	v_and_b32_e32 v187, 0xffff0000, v187
	v_pk_add_f32 v[136:137], v[136:137], v[186:187]
	v_pk_add_f32 v[134:135], v[134:135], v[198:199]
	v_lshlrev_b32_e32 v186, 16, v188
	v_and_b32_e32 v187, 0xffff0000, v188
	v_lshlrev_b32_e32 v188, 16, v189
	v_and_b32_e32 v189, 0xffff0000, v189
	v_pk_add_f32 v[188:189], v[128:129], v[188:189]
	v_pk_add_f32 v[186:187], v[126:127], v[186:187]
	v_cvt_pk_bf16_f32 v126, v134, v135
	v_cvt_pk_bf16_f32 v127, v136, v137
	v_cvt_pk_bf16_f32 v128, v186, v187
	v_cvt_pk_bf16_f32 v129, v188, v189
	global_store_dwordx4 v[194:195], v[126:129], off
	s_nop 1
	v_mul_f32_e32 v126, v135, v135
	v_mul_f32_e32 v127, v137, v137
	v_fmac_f32_e32 v126, v134, v134
	v_fmac_f32_e32 v127, v136, v136
	v_add_f32_e32 v126, v126, v127
	v_mul_f32_e32 v127, v187, v187
	v_mul_f32_e32 v128, v189, v189
	v_fmac_f32_e32 v127, v186, v186
	v_fmac_f32_e32 v128, v188, v188
	v_add_f32_e32 v127, v127, v128
	v_add_f32_e32 v134, v126, v127
	v_lshlrev_b32_e32 v126, 16, v190
	v_and_b32_e32 v127, 0xffff0000, v190
	v_lshlrev_b32_e32 v128, 16, v191
	v_and_b32_e32 v129, 0xffff0000, v191
	v_pk_add_f32 v[120:121], v[120:121], v[128:129]
	v_pk_add_f32 v[118:119], v[118:119], v[126:127]
	v_lshlrev_b32_e32 v126, 16, v192
	v_and_b32_e32 v127, 0xffff0000, v192
	v_lshlrev_b32_e32 v128, 16, v193
	v_and_b32_e32 v129, 0xffff0000, v193
	v_pk_add_f32 v[128:129], v[116:117], v[128:129]
	v_pk_add_f32 v[126:127], v[114:115], v[126:127]
	v_cvt_pk_bf16_f32 v114, v118, v119
	v_cvt_pk_bf16_f32 v115, v120, v121
	v_cvt_pk_bf16_f32 v116, v126, v127
	v_cvt_pk_bf16_f32 v117, v128, v129
	global_store_dwordx4 v[196:197], v[114:117], off
	s_nop 1
	v_mul_f32_e32 v114, v119, v119
	v_mul_f32_e32 v115, v121, v121
	v_fmac_f32_e32 v114, v118, v118
	v_fmac_f32_e32 v115, v120, v120
	v_add_f32_e32 v114, v114, v115
	v_mul_f32_e32 v115, v127, v127
	v_mul_f32_e32 v116, v129, v129
	v_fmac_f32_e32 v115, v126, v126
	v_fmac_f32_e32 v116, v128, v128
	v_add_f32_e32 v115, v115, v116
	v_add_f32_e32 v114, v114, v115
	v_and_b32_e32 v116, 64, v205
	v_add_f32_e32 v115, v134, v114
	v_xor_b32_e32 v114, 16, v205
	v_add_u32_e32 v116, 64, v116
	v_cmp_lt_i32_e32 vcc, v114, v116
	s_nop 1
	v_cndmask_b32_e32 v114, v205, v114, vcc
	v_lshlrev_b32_e32 v114, 2, v114
	s_waitcnt lgkmcnt(0)
	v_mov_b32_e32 v116, v115
	s_nop 1
	v_permlane16_swap_b32_e32 v115, v116
	v_add_f32_e32 v115, v115, v116
	v_mov_b32_e32 v116, v115
	s_nop 1
	v_permlane32_swap_b32_e32 v115, v116
	s_and_saveexec_b64 s[52:53], s[38:39]
	s_cbranch_execz .LBB0_1306
	v_mov_b32_e32 v169, v49
	v_lshl_add_u64 v[118:119], v[168:169], 2, s[22:23]
	v_add_f32_e32 v115, v115, v116
	global_store_dword v[118:119], v115, off

.LBB0_1312:
	s_or_b64 exec, exec, s[52:53]
	v_add_u32_e32 v66, 0x20000, v48
	v_mov_b32_e32 v67, v49
	v_lshl_add_u64 v[112:113], v[66:67], 1, s[16:17]
	v_add_u32_e32 v66, 0x20080, v48
	v_lshl_add_u64 v[106:107], v[66:67], 1, s[16:17]
	v_add_u32_e32 v66, 0x24000, v48
	v_lshl_add_u64 v[104:105], v[66:67], 1, s[16:17]
	v_add_u32_e32 v66, 0x24080, v48
	v_lshl_add_u64 v[102:103], v[66:67], 1, s[16:17]
	v_add_u32_e32 v66, 0x28000, v48
	v_lshl_add_u64 v[100:101], v[66:67], 1, s[16:17]
	v_add_u32_e32 v66, 0x28080, v48
	v_lshl_add_u64 v[98:99], v[66:67], 1, s[16:17]
	v_add_u32_e32 v66, 0x2c000, v48
	v_add_u32_e32 v48, 0x2c080, v48
	v_lshl_add_u64 v[96:97], v[66:67], 1, s[16:17]
	v_lshl_add_u64 v[94:95], v[48:49], 1, s[16:17]
	s_waitcnt vmcnt(4)
	v_lshlrev_b32_e32 v116, 16, v212
	v_and_b32_e32 v117, 0xffff0000, v212
	v_lshlrev_b32_e32 v108, 16, v213
	v_and_b32_e32 v109, 0xffff0000, v213
	v_pk_add_f32 v[64:65], v[64:65], v[108:109]
	v_pk_add_f32 v[62:63], v[62:63], v[116:117]
	v_lshlrev_b32_e32 v108, 16, v214
	v_and_b32_e32 v109, 0xffff0000, v214
	v_lshlrev_b32_e32 v110, 16, v215
	v_and_b32_e32 v111, 0xffff0000, v215
	v_pk_add_f32 v[110:111], v[60:61], v[110:111]
	v_pk_add_f32 v[108:109], v[58:59], v[108:109]
	v_cvt_pk_bf16_f32 v58, v62, v63
	v_cvt_pk_bf16_f32 v59, v64, v65
	v_cvt_pk_bf16_f32 v60, v108, v109
	v_cvt_pk_bf16_f32 v61, v110, v111
	global_store_dwordx4 v[112:113], v[58:61], off
	s_nop 1
	v_mul_f32_e32 v48, v63, v63
	v_mul_f32_e32 v58, v65, v65
	v_fmac_f32_e32 v48, v62, v62
	v_fmac_f32_e32 v58, v64, v64
	v_add_f32_e32 v48, v48, v58
	v_mul_f32_e32 v58, v109, v109
	v_mul_f32_e32 v59, v111, v111
	v_fmac_f32_e32 v58, v108, v108
	v_fmac_f32_e32 v59, v110, v110
	v_add_f32_e32 v58, v58, v59
	v_add_f32_e32 v48, v48, v58
	v_lshlrev_b32_e32 v58, 16, v216
	v_and_b32_e32 v59, 0xffff0000, v216
	v_lshlrev_b32_e32 v60, 16, v217
	v_and_b32_e32 v61, 0xffff0000, v217
	v_pk_add_f32 v[56:57], v[56:57], v[60:61]
	v_pk_add_f32 v[54:55], v[54:55], v[58:59]
	v_lshlrev_b32_e32 v58, 16, v218
	v_and_b32_e32 v59, 0xffff0000, v218
	v_lshlrev_b32_e32 v60, 16, v219
	v_and_b32_e32 v61, 0xffff0000, v219
	v_pk_add_f32 v[60:61], v[52:53], v[60:61]
	v_pk_add_f32 v[58:59], v[50:51], v[58:59]
	v_cvt_pk_bf16_f32 v50, v54, v55
	v_cvt_pk_bf16_f32 v51, v56, v57
	v_cvt_pk_bf16_f32 v52, v58, v59
	v_cvt_pk_bf16_f32 v53, v60, v61
	global_store_dwordx4 v[106:107], v[50:53], off
	s_nop 1
	v_mul_f32_e32 v50, v55, v55
	v_mul_f32_e32 v51, v57, v57
	v_fmac_f32_e32 v50, v54, v54
	v_fmac_f32_e32 v51, v56, v56
	v_add_f32_e32 v50, v50, v51
	v_mul_f32_e32 v51, v59, v59
	v_mul_f32_e32 v52, v61, v61
	v_fmac_f32_e32 v51, v58, v58
	v_fmac_f32_e32 v52, v60, v60
	v_add_f32_e32 v51, v51, v52
	v_add_f32_e32 v50, v50, v51
	v_add_f32_e32 v48, v48, v50
	ds_bpermute_b32 v50, v114, v48
	s_waitcnt lgkmcnt(0)
	v_add_f32_e32 v50, v48, v50
	v_mov_b32_e32 v51, v50
	s_nop 1
	v_permlane32_swap_b32_e32 v50, v51
	s_and_saveexec_b64 s[52:53], s[38:39]
	s_cbranch_execz .LBB0_1314
	v_add_u32_e32 v48, 0x80, v168
	v_lshl_add_u64 v[52:53], v[48:49], 2, s[22:23]
	v_add_f32_e32 v48, v50, v51
	global_store_dword v[52:53], v48, off
.LBB0_1314:
	s_or_b64 exec, exec, s[52:53]
	v_lshlrev_b32_e32 v50, 16, v220
	v_and_b32_e32 v51, 0xffff0000, v220
	v_lshlrev_b32_e32 v52, 16, v221
	v_and_b32_e32 v53, 0xffff0000, v221
	v_pk_add_f32 v[46:47], v[46:47], v[52:53]
	v_pk_add_f32 v[44:45], v[44:45], v[50:51]
	v_lshlrev_b32_e32 v50, 16, v222
	v_and_b32_e32 v51, 0xffff0000, v222
	v_lshlrev_b32_e32 v52, 16, v223
	v_and_b32_e32 v53, 0xffff0000, v223
	v_pk_add_f32 v[52:53], v[42:43], v[52:53]
	v_pk_add_f32 v[50:51], v[40:41], v[50:51]
	v_cvt_pk_bf16_f32 v40, v44, v45
	v_cvt_pk_bf16_f32 v41, v46, v47
	v_cvt_pk_bf16_f32 v42, v50, v51
	v_cvt_pk_bf16_f32 v43, v52, v53
	global_store_dwordx4 v[104:105], v[40:43], off
	s_nop 1
	v_mul_f32_e32 v40, v45, v45
	v_mul_f32_e32 v41, v47, v47
	v_fmac_f32_e32 v40, v44, v44
	v_fmac_f32_e32 v41, v46, v46
	v_add_f32_e32 v40, v40, v41
	v_mul_f32_e32 v41, v51, v51
	v_mul_f32_e32 v42, v53, v53
	v_fmac_f32_e32 v41, v50, v50
	v_fmac_f32_e32 v42, v52, v52
	v_add_f32_e32 v41, v41, v42
	v_add_f32_e32 v44, v40, v41
	v_lshlrev_b32_e32 v40, 16, v224
	v_and_b32_e32 v41, 0xffff0000, v224
	v_lshlrev_b32_e32 v42, 16, v225
	v_and_b32_e32 v43, 0xffff0000, v225
	v_pk_add_f32 v[38:39], v[38:39], v[42:43]
	v_pk_add_f32 v[36:37], v[36:37], v[40:41]
	v_lshlrev_b32_e32 v40, 16, v226
	v_and_b32_e32 v41, 0xffff0000, v226
	v_lshlrev_b32_e32 v42, 16, v227
	v_and_b32_e32 v43, 0xffff0000, v227
	v_pk_add_f32 v[42:43], v[34:35], v[42:43]
	v_pk_add_f32 v[34:35], v[32:33], v[40:41]
	v_mul_f32_e32 v33, v37, v37
	v_cvt_pk_bf16_f32 v32, v36, v37
	v_fmac_f32_e32 v33, v36, v36
	v_mul_f32_e32 v36, v39, v39
	v_fmac_f32_e32 v36, v38, v38
	v_add_f32_e32 v33, v33, v36
	v_mul_f32_e32 v36, v35, v35
	v_mul_f32_e32 v37, v43, v43
	v_fmac_f32_e32 v36, v34, v34
	v_fmac_f32_e32 v37, v42, v42
	v_add_f32_e32 v36, v36, v37
	v_add_f32_e32 v33, v33, v36
	v_add_f32_e32 v36, v44, v33
	ds_bpermute_b32 v37, v114, v36
	v_cvt_pk_bf16_f32 v33, v38, v39
	v_cvt_pk_bf16_f32 v34, v34, v35
	v_cvt_pk_bf16_f32 v35, v42, v43
	global_store_dwordx4 v[102:103], v[32:35], off
	s_nop 1
	s_waitcnt lgkmcnt(0)
	v_add_f32_e32 v32, v36, v37
	v_mov_b32_e32 v33, v32
	s_nop 1
	v_permlane32_swap_b32_e32 v32, v33
	s_and_saveexec_b64 s[52:53], s[38:39]
	s_cbranch_execz .LBB0_1316
	v_add_u32_e32 v48, 0x90, v168
	v_lshl_add_u64 v[34:35], v[48:49], 2, s[22:23]
	v_add_f32_e32 v32, v32, v33
	global_store_dword v[34:35], v32, off
.LBB0_1316:
	s_or_b64 exec, exec, s[52:53]
	v_lshlrev_b32_e32 v32, 16, v228
	v_and_b32_e32 v33, 0xffff0000, v228
	v_lshlrev_b32_e32 v34, 16, v229
	v_and_b32_e32 v35, 0xffff0000, v229
	v_pk_add_f32 v[30:31], v[30:31], v[34:35]
	v_pk_add_f32 v[28:29], v[28:29], v[32:33]
	v_lshlrev_b32_e32 v32, 16, v230
	v_and_b32_e32 v33, 0xffff0000, v230
	v_lshlrev_b32_e32 v34, 16, v231
	v_and_b32_e32 v35, 0xffff0000, v231
	v_pk_add_f32 v[34:35], v[26:27], v[34:35]
	v_pk_add_f32 v[32:33], v[24:25], v[32:33]
	v_cvt_pk_bf16_f32 v24, v28, v29
	v_cvt_pk_bf16_f32 v25, v30, v31
	v_cvt_pk_bf16_f32 v26, v32, v33
	v_cvt_pk_bf16_f32 v27, v34, v35
	global_store_dwordx4 v[100:101], v[24:27], off
	s_nop 1
	v_mul_f32_e32 v24, v29, v29
	v_mul_f32_e32 v25, v31, v31
	v_fmac_f32_e32 v24, v28, v28
	v_fmac_f32_e32 v25, v30, v30
	v_add_f32_e32 v24, v24, v25
	v_mul_f32_e32 v25, v33, v33
	v_mul_f32_e32 v26, v35, v35
	v_fmac_f32_e32 v25, v32, v32
	v_fmac_f32_e32 v26, v34, v34
	v_add_f32_e32 v25, v25, v26
	v_add_f32_e32 v28, v24, v25
	v_lshlrev_b32_e32 v24, 16, v232
	v_and_b32_e32 v25, 0xffff0000, v232
	v_lshlrev_b32_e32 v26, 16, v233
	v_and_b32_e32 v27, 0xffff0000, v233
	v_pk_add_f32 v[22:23], v[22:23], v[26:27]
	v_pk_add_f32 v[20:21], v[20:21], v[24:25]
	v_lshlrev_b32_e32 v24, 16, v234
	v_and_b32_e32 v25, 0xffff0000, v234
	v_lshlrev_b32_e32 v26, 16, v235
	v_and_b32_e32 v27, 0xffff0000, v235
	v_pk_add_f32 v[26:27], v[18:19], v[26:27]
	v_pk_add_f32 v[18:19], v[16:17], v[24:25]
	v_mul_f32_e32 v17, v21, v21
	v_cvt_pk_bf16_f32 v16, v20, v21
	v_fmac_f32_e32 v17, v20, v20
	v_mul_f32_e32 v20, v23, v23
	v_fmac_f32_e32 v20, v22, v22
	v_add_f32_e32 v17, v17, v20
	v_mul_f32_e32 v20, v19, v19
	v_mul_f32_e32 v21, v27, v27
	v_fmac_f32_e32 v20, v18, v18
	v_fmac_f32_e32 v21, v26, v26
	v_add_f32_e32 v20, v20, v21
	v_add_f32_e32 v17, v17, v20
	v_add_f32_e32 v20, v28, v17
	ds_bpermute_b32 v21, v114, v20
	v_cvt_pk_bf16_f32 v17, v22, v23
	v_cvt_pk_bf16_f32 v18, v18, v19
	v_cvt_pk_bf16_f32 v19, v26, v27
	global_store_dwordx4 v[98:99], v[16:19], off
	s_nop 1
	s_waitcnt lgkmcnt(0)
	v_add_f32_e32 v16, v20, v21
	v_mov_b32_e32 v17, v16
	s_nop 1
	v_permlane32_swap_b32_e32 v16, v17
	s_and_saveexec_b64 s[52:53], s[38:39]
	s_cbranch_execz .LBB0_1318
	v_add_u32_e32 v48, 0xa0, v168
	v_lshl_add_u64 v[18:19], v[48:49], 2, s[22:23]
	v_add_f32_e32 v16, v16, v17
	global_store_dword v[18:19], v16, off
.LBB0_1318:
	s_or_b64 exec, exec, s[52:53]
	v_lshlrev_b32_e32 v16, 16, v236
	v_and_b32_e32 v17, 0xffff0000, v236
	v_lshlrev_b32_e32 v18, 16, v237
	v_and_b32_e32 v19, 0xffff0000, v237
	v_pk_add_f32 v[14:15], v[14:15], v[18:19]
	v_pk_add_f32 v[12:13], v[12:13], v[16:17]
	v_lshlrev_b32_e32 v16, 16, v238
	v_and_b32_e32 v17, 0xffff0000, v238
	v_lshlrev_b32_e32 v18, 16, v239
	v_and_b32_e32 v19, 0xffff0000, v239
	v_pk_add_f32 v[18:19], v[10:11], v[18:19]
	v_pk_add_f32 v[16:17], v[8:9], v[16:17]
	v_cvt_pk_bf16_f32 v8, v12, v13
	v_cvt_pk_bf16_f32 v9, v14, v15
	v_cvt_pk_bf16_f32 v10, v16, v17
	v_cvt_pk_bf16_f32 v11, v18, v19
	global_store_dwordx4 v[96:97], v[8:11], off
	s_nop 1
	v_mul_f32_e32 v8, v13, v13
	v_mul_f32_e32 v9, v15, v15
	v_fmac_f32_e32 v8, v12, v12
	v_fmac_f32_e32 v9, v14, v14
	v_add_f32_e32 v8, v8, v9
	v_mul_f32_e32 v9, v17, v17
	v_mul_f32_e32 v10, v19, v19
	v_fmac_f32_e32 v9, v16, v16
	v_fmac_f32_e32 v10, v18, v18
	v_add_f32_e32 v9, v9, v10
	v_add_f32_e32 v12, v8, v9
	v_lshlrev_b32_e32 v8, 16, v240
	v_and_b32_e32 v9, 0xffff0000, v240
	v_lshlrev_b32_e32 v10, 16, v241
	v_and_b32_e32 v11, 0xffff0000, v241
	v_pk_add_f32 v[6:7], v[6:7], v[10:11]
	v_pk_add_f32 v[4:5], v[4:5], v[8:9]
	v_lshlrev_b32_e32 v8, 16, v242
	v_and_b32_e32 v9, 0xffff0000, v242
	v_lshlrev_b32_e32 v10, 16, v243
	v_and_b32_e32 v11, 0xffff0000, v243
	v_pk_add_f32 v[10:11], v[2:3], v[10:11]
	v_pk_add_f32 v[2:3], v[0:1], v[8:9]
	v_mul_f32_e32 v1, v5, v5
	v_cvt_pk_bf16_f32 v0, v4, v5
	v_fmac_f32_e32 v1, v4, v4
	v_mul_f32_e32 v4, v7, v7
	v_fmac_f32_e32 v4, v6, v6
	v_add_f32_e32 v1, v1, v4
	v_mul_f32_e32 v4, v3, v3
	v_mul_f32_e32 v5, v11, v11
	v_fmac_f32_e32 v4, v2, v2
	v_fmac_f32_e32 v5, v10, v10
	v_add_f32_e32 v4, v4, v5
	v_add_f32_e32 v1, v1, v4
	v_add_f32_e32 v4, v12, v1
	ds_bpermute_b32 v5, v114, v4
	v_cvt_pk_bf16_f32 v1, v6, v7
	v_cvt_pk_bf16_f32 v2, v2, v3
	v_cvt_pk_bf16_f32 v3, v10, v11
	global_store_dwordx4 v[94:95], v[0:3], off
	s_nop 1
	s_waitcnt lgkmcnt(0)
	v_add_f32_e32 v0, v4, v5
	v_mov_b32_e32 v1, v0
	s_nop 1
	v_permlane32_swap_b32_e32 v0, v1
	s_and_saveexec_b64 s[52:53], s[38:39]
	s_cbranch_execz .LBB0_1320
	v_add_u32_e32 v48, 0xb0, v168
	v_lshl_add_u64 v[2:3], v[48:49], 2, s[22:23]
	v_add_f32_e32 v0, v0, v1
	global_store_dword v[2:3], v0, off

.LBB0_1981:
	v_lshl_add_u32 v122, s33, 8, v182
	s_lshl_b32 s6, s18, 8
	v_lshl_add_u32 v48, v122, 10, s6
	v_or_b32_e32 v48, v48, v184
	v_lshl_add_u64 v[194:195], v[48:49], 1, s[16:17]
	global_load_dwordx4 v[186:189], v[194:195], off
	s_lshl_b32 s6, s18, 16
	s_or_b32 s6, s6, s62
	v_add_u32_e32 v168, s6, v122
	v_or_b32_e32 v122, 0x80, v48
	v_mov_b32_e32 v123, v49
	v_lshl_add_u64 v[196:197], v[122:123], 1, s[16:17]
	global_load_dwordx4 v[190:193], v[196:197], off
	v_add_u32_e32 v122, 0x4000, v48
	v_lshl_add_u64 v[180:181], v[122:123], 1, s[16:17]
	v_add_u32_e32 v122, 0x4080, v48
	v_lshl_add_u64 v[178:179], v[122:123], 1, s[16:17]
	v_add_u32_e32 v122, 0x8000, v48
	v_lshl_add_u64 v[176:177], v[122:123], 1, s[16:17]
	v_add_u32_e32 v122, 0x8080, v48
	v_lshl_add_u64 v[174:175], v[122:123], 1, s[16:17]
	v_add_u32_e32 v122, 0xc000, v48
	v_add_u32_e32 v130, 0xc080, v48
	v_mov_b32_e32 v131, v49
	v_lshl_add_u64 v[172:173], v[122:123], 1, s[16:17]
	v_lshl_add_u64 v[170:171], v[130:131], 1, s[16:17]
	global_load_dwordx4 v[150:153], v[180:181], off
	global_load_dwordx4 v[146:149], v[178:179], off
	global_load_dwordx4 v[142:145], v[176:177], off
	global_load_dwordx4 v[138:141], v[174:175], off
	global_load_dwordx4 v[122:125], v[172:173], off
	global_load_dwordx4 v[130:133], v[170:171], off
	v_mov_b32_e32 v245, v49
	v_add_u32_e32 v244, 0x20000, v48
	v_lshl_add_u64 v[156:157], v[244:245], 1, s[16:17]
	global_load_dwordx4 v[212:215], v[156:157], off
	v_add_u32_e32 v244, 0x20080, v48
	v_lshl_add_u64 v[158:159], v[244:245], 1, s[16:17]
	global_load_dwordx4 v[216:219], v[158:159], off
	v_add_u32_e32 v244, 0x24000, v48
	v_lshl_add_u64 v[160:161], v[244:245], 1, s[16:17]
	global_load_dwordx4 v[220:223], v[160:161], off
	v_add_u32_e32 v244, 0x24080, v48
	v_lshl_add_u64 v[162:163], v[244:245], 1, s[16:17]
	global_load_dwordx4 v[224:227], v[162:163], off
	v_add_u32_e32 v244, 0x28000, v48
	v_lshl_add_u64 v[164:165], v[244:245], 1, s[16:17]
	global_load_dwordx4 v[228:231], v[164:165], off
	v_add_u32_e32 v244, 0x28080, v48
	v_lshl_add_u64 v[166:167], v[244:245], 1, s[16:17]
	global_load_dwordx4 v[232:235], v[166:167], off
	v_add_u32_e32 v244, 0x2c000, v48
	v_lshl_add_u64 v[248:249], v[244:245], 1, s[16:17]
	global_load_dwordx4 v[236:239], v[248:249], off
	v_add_u32_e32 v244, 0x2c080, v48
	v_lshl_add_u64 v[250:251], v[244:245], 1, s[16:17]
	global_load_dwordx4 v[240:243], v[250:251], off
	s_waitcnt vmcnt(8)
	v_lshlrev_b32_e32 v198, 16, v186
	v_and_b32_e32 v199, 0xffff0000, v186
	v_lshlrev_b32_e32 v186, 16, v187
	v_and_b32_e32 v187, 0xffff0000, v187
	v_pk_fma_f32 v[136:137], v[136:137], 0.5, v[186:187] op_sel_hi:[1,0,1]
	v_pk_fma_f32 v[134:135], v[134:135], 0.5, v[198:199] op_sel_hi:[1,0,1]
	v_lshlrev_b32_e32 v186, 16, v188
	v_and_b32_e32 v187, 0xffff0000, v188
	v_lshlrev_b32_e32 v188, 16, v189
	v_and_b32_e32 v189, 0xffff0000, v189
	v_pk_fma_f32 v[188:189], v[128:129], 0.5, v[188:189] op_sel_hi:[1,0,1]
	v_pk_fma_f32 v[186:187], v[126:127], 0.5, v[186:187] op_sel_hi:[1,0,1]
	v_cvt_pk_bf16_f32 v126, v134, v135
	v_cvt_pk_bf16_f32 v127, v136, v137
	v_cvt_pk_bf16_f32 v128, v186, v187
	v_cvt_pk_bf16_f32 v129, v188, v189
	global_store_dwordx4 v[194:195], v[126:129], off
	s_nop 1
	v_mul_f32_e32 v126, v135, v135
	v_mul_f32_e32 v127, v137, v137
	v_fmac_f32_e32 v126, v134, v134
	v_fmac_f32_e32 v127, v136, v136
	v_add_f32_e32 v126, v126, v127
	v_mul_f32_e32 v127, v187, v187
	v_mul_f32_e32 v128, v189, v189
	v_fmac_f32_e32 v127, v186, v186
	v_fmac_f32_e32 v128, v188, v188
	v_add_f32_e32 v127, v127, v128
	v_add_f32_e32 v134, v126, v127
	v_lshlrev_b32_e32 v126, 16, v190
	v_and_b32_e32 v127, 0xffff0000, v190
	v_lshlrev_b32_e32 v128, 16, v191
	v_and_b32_e32 v129, 0xffff0000, v191
	v_pk_fma_f32 v[120:121], v[120:121], 0.5, v[128:129] op_sel_hi:[1,0,1]
	v_pk_fma_f32 v[118:119], v[118:119], 0.5, v[126:127] op_sel_hi:[1,0,1]
	v_lshlrev_b32_e32 v126, 16, v192
	v_and_b32_e32 v127, 0xffff0000, v192
	v_lshlrev_b32_e32 v128, 16, v193
	v_and_b32_e32 v129, 0xffff0000, v193
	v_pk_fma_f32 v[128:129], v[116:117], 0.5, v[128:129] op_sel_hi:[1,0,1]
	v_pk_fma_f32 v[126:127], v[114:115], 0.5, v[126:127] op_sel_hi:[1,0,1]
	v_cvt_pk_bf16_f32 v114, v118, v119
	v_cvt_pk_bf16_f32 v115, v120, v121
	v_cvt_pk_bf16_f32 v116, v126, v127
	v_cvt_pk_bf16_f32 v117, v128, v129
	global_store_dwordx4 v[196:197], v[114:117], off
	s_nop 1
	v_mul_f32_e32 v114, v119, v119
	v_mul_f32_e32 v115, v121, v121
	v_fmac_f32_e32 v114, v118, v118
	v_fmac_f32_e32 v115, v120, v120
	v_add_f32_e32 v114, v114, v115
	v_mul_f32_e32 v115, v127, v127
	v_mul_f32_e32 v116, v129, v129
	v_fmac_f32_e32 v115, v126, v126
	v_fmac_f32_e32 v116, v128, v128
	v_add_f32_e32 v115, v115, v116
	v_add_f32_e32 v114, v114, v115
	v_and_b32_e32 v116, 64, v205
	v_add_f32_e32 v115, v134, v114
	v_xor_b32_e32 v114, 16, v205
	v_add_u32_e32 v116, 64, v116
	v_cmp_lt_i32_e32 vcc, v114, v116
	s_nop 1
	v_cndmask_b32_e32 v114, v205, v114, vcc
	v_lshlrev_b32_e32 v114, 2, v114
	s_waitcnt lgkmcnt(0)
	v_mov_b32_e32 v116, v115
	s_nop 1
	v_permlane16_swap_b32_e32 v115, v116
	v_add_f32_e32 v115, v115, v116
	v_mov_b32_e32 v116, v115
	s_nop 1
	v_permlane32_swap_b32_e32 v115, v116
	s_and_saveexec_b64 s[48:49], s[38:39]
	s_cbranch_execz .LBB0_1983
	v_mov_b32_e32 v169, v49
	v_lshl_add_u64 v[118:119], v[168:169], 2, s[22:23]
	v_add_f32_e32 v115, v115, v116
	global_store_dword v[118:119], v115, off

.LBB0_1989:
	s_or_b64 exec, exec, s[48:49]
	v_add_u32_e32 v66, 0x20000, v48
	v_mov_b32_e32 v67, v49
	v_lshl_add_u64 v[112:113], v[66:67], 1, s[16:17]
	v_add_u32_e32 v66, 0x20080, v48
	v_lshl_add_u64 v[106:107], v[66:67], 1, s[16:17]
	v_add_u32_e32 v66, 0x24000, v48
	v_lshl_add_u64 v[104:105], v[66:67], 1, s[16:17]
	v_add_u32_e32 v66, 0x24080, v48
	v_lshl_add_u64 v[102:103], v[66:67], 1, s[16:17]
	v_add_u32_e32 v66, 0x28000, v48
	v_lshl_add_u64 v[100:101], v[66:67], 1, s[16:17]
	v_add_u32_e32 v66, 0x28080, v48
	v_lshl_add_u64 v[98:99], v[66:67], 1, s[16:17]
	v_add_u32_e32 v66, 0x2c000, v48
	v_add_u32_e32 v48, 0x2c080, v48
	v_lshl_add_u64 v[96:97], v[66:67], 1, s[16:17]
	v_lshl_add_u64 v[94:95], v[48:49], 1, s[16:17]
	s_waitcnt vmcnt(4)
	v_lshlrev_b32_e32 v116, 16, v212
	v_and_b32_e32 v117, 0xffff0000, v212
	v_lshlrev_b32_e32 v108, 16, v213
	v_and_b32_e32 v109, 0xffff0000, v213
	v_pk_fma_f32 v[64:65], v[64:65], 0.5, v[108:109] op_sel_hi:[1,0,1]
	v_pk_fma_f32 v[62:63], v[62:63], 0.5, v[116:117] op_sel_hi:[1,0,1]
	v_lshlrev_b32_e32 v108, 16, v214
	v_and_b32_e32 v109, 0xffff0000, v214
	v_lshlrev_b32_e32 v110, 16, v215
	v_and_b32_e32 v111, 0xffff0000, v215
	v_pk_fma_f32 v[110:111], v[60:61], 0.5, v[110:111] op_sel_hi:[1,0,1]
	v_pk_fma_f32 v[108:109], v[58:59], 0.5, v[108:109] op_sel_hi:[1,0,1]
	v_cvt_pk_bf16_f32 v58, v62, v63
	v_cvt_pk_bf16_f32 v59, v64, v65
	v_cvt_pk_bf16_f32 v60, v108, v109
	v_cvt_pk_bf16_f32 v61, v110, v111
	global_store_dwordx4 v[112:113], v[58:61], off
	s_nop 1
	v_mul_f32_e32 v48, v63, v63
	v_mul_f32_e32 v58, v65, v65
	v_fmac_f32_e32 v48, v62, v62
	v_fmac_f32_e32 v58, v64, v64
	v_add_f32_e32 v48, v48, v58
	v_mul_f32_e32 v58, v109, v109
	v_mul_f32_e32 v59, v111, v111
	v_fmac_f32_e32 v58, v108, v108
	v_fmac_f32_e32 v59, v110, v110
	v_add_f32_e32 v58, v58, v59
	v_add_f32_e32 v48, v48, v58
	v_lshlrev_b32_e32 v58, 16, v216
	v_and_b32_e32 v59, 0xffff0000, v216
	v_lshlrev_b32_e32 v60, 16, v217
	v_and_b32_e32 v61, 0xffff0000, v217
	v_pk_fma_f32 v[56:57], v[56:57], 0.5, v[60:61] op_sel_hi:[1,0,1]
	v_pk_fma_f32 v[54:55], v[54:55], 0.5, v[58:59] op_sel_hi:[1,0,1]
	v_lshlrev_b32_e32 v58, 16, v218
	v_and_b32_e32 v59, 0xffff0000, v218
	v_lshlrev_b32_e32 v60, 16, v219
	v_and_b32_e32 v61, 0xffff0000, v219
	v_pk_fma_f32 v[60:61], v[52:53], 0.5, v[60:61] op_sel_hi:[1,0,1]
	v_pk_fma_f32 v[58:59], v[50:51], 0.5, v[58:59] op_sel_hi:[1,0,1]
	v_cvt_pk_bf16_f32 v50, v54, v55
	v_cvt_pk_bf16_f32 v51, v56, v57
	v_cvt_pk_bf16_f32 v52, v58, v59
	v_cvt_pk_bf16_f32 v53, v60, v61
	global_store_dwordx4 v[106:107], v[50:53], off
	s_nop 1
	v_mul_f32_e32 v50, v55, v55
	v_mul_f32_e32 v51, v57, v57
	v_fmac_f32_e32 v50, v54, v54
	v_fmac_f32_e32 v51, v56, v56
	v_add_f32_e32 v50, v50, v51
	v_mul_f32_e32 v51, v59, v59
	v_mul_f32_e32 v52, v61, v61
	v_fmac_f32_e32 v51, v58, v58
	v_fmac_f32_e32 v52, v60, v60
	v_add_f32_e32 v51, v51, v52
	v_add_f32_e32 v50, v50, v51
	v_add_f32_e32 v48, v48, v50
	ds_bpermute_b32 v50, v114, v48
	s_waitcnt lgkmcnt(0)
	v_add_f32_e32 v50, v48, v50
	v_mov_b32_e32 v51, v50
	s_nop 1
	v_permlane32_swap_b32_e32 v50, v51
	s_and_saveexec_b64 s[48:49], s[38:39]
	s_cbranch_execz .LBB0_1991
	v_add_u32_e32 v48, 0x80, v168
	v_lshl_add_u64 v[52:53], v[48:49], 2, s[22:23]
	v_add_f32_e32 v48, v50, v51
	global_store_dword v[52:53], v48, off
.LBB0_1991:
	s_or_b64 exec, exec, s[48:49]
	v_lshlrev_b32_e32 v50, 16, v220
	v_and_b32_e32 v51, 0xffff0000, v220
	v_lshlrev_b32_e32 v52, 16, v221
	v_and_b32_e32 v53, 0xffff0000, v221
	v_pk_fma_f32 v[46:47], v[46:47], 0.5, v[52:53] op_sel_hi:[1,0,1]
	v_pk_fma_f32 v[44:45], v[44:45], 0.5, v[50:51] op_sel_hi:[1,0,1]
	v_lshlrev_b32_e32 v50, 16, v222
	v_and_b32_e32 v51, 0xffff0000, v222
	v_lshlrev_b32_e32 v52, 16, v223
	v_and_b32_e32 v53, 0xffff0000, v223
	v_pk_fma_f32 v[52:53], v[42:43], 0.5, v[52:53] op_sel_hi:[1,0,1]
	v_pk_fma_f32 v[50:51], v[40:41], 0.5, v[50:51] op_sel_hi:[1,0,1]
	v_cvt_pk_bf16_f32 v40, v44, v45
	v_cvt_pk_bf16_f32 v41, v46, v47
	v_cvt_pk_bf16_f32 v42, v50, v51
	v_cvt_pk_bf16_f32 v43, v52, v53
	global_store_dwordx4 v[104:105], v[40:43], off
	s_nop 1
	v_mul_f32_e32 v40, v45, v45
	v_mul_f32_e32 v41, v47, v47
	v_fmac_f32_e32 v40, v44, v44
	v_fmac_f32_e32 v41, v46, v46
	v_add_f32_e32 v40, v40, v41
	v_mul_f32_e32 v41, v51, v51
	v_mul_f32_e32 v42, v53, v53
	v_fmac_f32_e32 v41, v50, v50
	v_fmac_f32_e32 v42, v52, v52
	v_add_f32_e32 v41, v41, v42
	v_add_f32_e32 v44, v40, v41
	v_lshlrev_b32_e32 v40, 16, v224
	v_and_b32_e32 v41, 0xffff0000, v224
	v_lshlrev_b32_e32 v42, 16, v225
	v_and_b32_e32 v43, 0xffff0000, v225
	v_pk_fma_f32 v[38:39], v[38:39], 0.5, v[42:43] op_sel_hi:[1,0,1]
	v_pk_fma_f32 v[36:37], v[36:37], 0.5, v[40:41] op_sel_hi:[1,0,1]
	v_lshlrev_b32_e32 v40, 16, v226
	v_and_b32_e32 v41, 0xffff0000, v226
	v_lshlrev_b32_e32 v42, 16, v227
	v_and_b32_e32 v43, 0xffff0000, v227
	v_pk_fma_f32 v[42:43], v[34:35], 0.5, v[42:43] op_sel_hi:[1,0,1]
	v_pk_fma_f32 v[34:35], v[32:33], 0.5, v[40:41] op_sel_hi:[1,0,1]
	v_mul_f32_e32 v33, v37, v37
	v_cvt_pk_bf16_f32 v32, v36, v37
	v_fmac_f32_e32 v33, v36, v36
	v_mul_f32_e32 v36, v39, v39
	v_fmac_f32_e32 v36, v38, v38
	v_add_f32_e32 v33, v33, v36
	v_mul_f32_e32 v36, v35, v35
	v_mul_f32_e32 v37, v43, v43
	v_fmac_f32_e32 v36, v34, v34
	v_fmac_f32_e32 v37, v42, v42
	v_add_f32_e32 v36, v36, v37
	v_add_f32_e32 v33, v33, v36
	v_add_f32_e32 v36, v44, v33
	ds_bpermute_b32 v37, v114, v36
	v_cvt_pk_bf16_f32 v33, v38, v39
	v_cvt_pk_bf16_f32 v34, v34, v35
	v_cvt_pk_bf16_f32 v35, v42, v43
	global_store_dwordx4 v[102:103], v[32:35], off
	s_nop 1
	s_waitcnt lgkmcnt(0)
	v_add_f32_e32 v32, v36, v37
	v_mov_b32_e32 v33, v32
	s_nop 1
	v_permlane32_swap_b32_e32 v32, v33
	s_and_saveexec_b64 s[48:49], s[38:39]
	s_cbranch_execz .LBB0_1993
	v_add_u32_e32 v48, 0x90, v168
	v_lshl_add_u64 v[34:35], v[48:49], 2, s[22:23]
	v_add_f32_e32 v32, v32, v33
	global_store_dword v[34:35], v32, off
.LBB0_1993:
	s_or_b64 exec, exec, s[48:49]
	v_lshlrev_b32_e32 v32, 16, v228
	v_and_b32_e32 v33, 0xffff0000, v228
	v_lshlrev_b32_e32 v34, 16, v229
	v_and_b32_e32 v35, 0xffff0000, v229
	v_pk_fma_f32 v[30:31], v[30:31], 0.5, v[34:35] op_sel_hi:[1,0,1]
	v_pk_fma_f32 v[28:29], v[28:29], 0.5, v[32:33] op_sel_hi:[1,0,1]
	v_lshlrev_b32_e32 v32, 16, v230
	v_and_b32_e32 v33, 0xffff0000, v230
	v_lshlrev_b32_e32 v34, 16, v231
	v_and_b32_e32 v35, 0xffff0000, v231
	v_pk_fma_f32 v[34:35], v[26:27], 0.5, v[34:35] op_sel_hi:[1,0,1]
	v_pk_fma_f32 v[32:33], v[24:25], 0.5, v[32:33] op_sel_hi:[1,0,1]
	v_cvt_pk_bf16_f32 v24, v28, v29
	v_cvt_pk_bf16_f32 v25, v30, v31
	v_cvt_pk_bf16_f32 v26, v32, v33
	v_cvt_pk_bf16_f32 v27, v34, v35
	global_store_dwordx4 v[100:101], v[24:27], off
	s_nop 1
	v_mul_f32_e32 v24, v29, v29
	v_mul_f32_e32 v25, v31, v31
	v_fmac_f32_e32 v24, v28, v28
	v_fmac_f32_e32 v25, v30, v30
	v_add_f32_e32 v24, v24, v25
	v_mul_f32_e32 v25, v33, v33
	v_mul_f32_e32 v26, v35, v35
	v_fmac_f32_e32 v25, v32, v32
	v_fmac_f32_e32 v26, v34, v34
	v_add_f32_e32 v25, v25, v26
	v_add_f32_e32 v28, v24, v25
	v_lshlrev_b32_e32 v24, 16, v232
	v_and_b32_e32 v25, 0xffff0000, v232
	v_lshlrev_b32_e32 v26, 16, v233
	v_and_b32_e32 v27, 0xffff0000, v233
	v_pk_fma_f32 v[22:23], v[22:23], 0.5, v[26:27] op_sel_hi:[1,0,1]
	v_pk_fma_f32 v[20:21], v[20:21], 0.5, v[24:25] op_sel_hi:[1,0,1]
	v_lshlrev_b32_e32 v24, 16, v234
	v_and_b32_e32 v25, 0xffff0000, v234
	v_lshlrev_b32_e32 v26, 16, v235
	v_and_b32_e32 v27, 0xffff0000, v235
	v_pk_fma_f32 v[26:27], v[18:19], 0.5, v[26:27] op_sel_hi:[1,0,1]
	v_pk_fma_f32 v[18:19], v[16:17], 0.5, v[24:25] op_sel_hi:[1,0,1]
	v_mul_f32_e32 v17, v21, v21
	v_cvt_pk_bf16_f32 v16, v20, v21
	v_fmac_f32_e32 v17, v20, v20
	v_mul_f32_e32 v20, v23, v23
	v_fmac_f32_e32 v20, v22, v22
	v_add_f32_e32 v17, v17, v20
	v_mul_f32_e32 v20, v19, v19
	v_mul_f32_e32 v21, v27, v27
	v_fmac_f32_e32 v20, v18, v18
	v_fmac_f32_e32 v21, v26, v26
	v_add_f32_e32 v20, v20, v21
	v_add_f32_e32 v17, v17, v20
	v_add_f32_e32 v20, v28, v17
	ds_bpermute_b32 v21, v114, v20
	v_cvt_pk_bf16_f32 v17, v22, v23
	v_cvt_pk_bf16_f32 v18, v18, v19
	v_cvt_pk_bf16_f32 v19, v26, v27
	global_store_dwordx4 v[98:99], v[16:19], off
	s_nop 1
	s_waitcnt lgkmcnt(0)
	v_add_f32_e32 v16, v20, v21
	v_mov_b32_e32 v17, v16
	s_nop 1
	v_permlane32_swap_b32_e32 v16, v17
	s_and_saveexec_b64 s[48:49], s[38:39]
	s_cbranch_execz .LBB0_1995
	v_add_u32_e32 v48, 0xa0, v168
	v_lshl_add_u64 v[18:19], v[48:49], 2, s[22:23]
	v_add_f32_e32 v16, v16, v17
	global_store_dword v[18:19], v16, off
.LBB0_1995:
	s_or_b64 exec, exec, s[48:49]
	v_lshlrev_b32_e32 v16, 16, v236
	v_and_b32_e32 v17, 0xffff0000, v236
	v_lshlrev_b32_e32 v18, 16, v237
	v_and_b32_e32 v19, 0xffff0000, v237
	v_pk_fma_f32 v[14:15], v[14:15], 0.5, v[18:19] op_sel_hi:[1,0,1]
	v_pk_fma_f32 v[12:13], v[12:13], 0.5, v[16:17] op_sel_hi:[1,0,1]
	v_lshlrev_b32_e32 v16, 16, v238
	v_and_b32_e32 v17, 0xffff0000, v238
	v_lshlrev_b32_e32 v18, 16, v239
	v_and_b32_e32 v19, 0xffff0000, v239
	v_pk_fma_f32 v[18:19], v[10:11], 0.5, v[18:19] op_sel_hi:[1,0,1]
	v_pk_fma_f32 v[16:17], v[8:9], 0.5, v[16:17] op_sel_hi:[1,0,1]
	v_cvt_pk_bf16_f32 v8, v12, v13
	v_cvt_pk_bf16_f32 v9, v14, v15
	v_cvt_pk_bf16_f32 v10, v16, v17
	v_cvt_pk_bf16_f32 v11, v18, v19
	global_store_dwordx4 v[96:97], v[8:11], off
	s_nop 1
	v_mul_f32_e32 v8, v13, v13
	v_mul_f32_e32 v9, v15, v15
	v_fmac_f32_e32 v8, v12, v12
	v_fmac_f32_e32 v9, v14, v14
	v_add_f32_e32 v8, v8, v9
	v_mul_f32_e32 v9, v17, v17
	v_mul_f32_e32 v10, v19, v19
	v_fmac_f32_e32 v9, v16, v16
	v_fmac_f32_e32 v10, v18, v18
	v_add_f32_e32 v9, v9, v10
	v_add_f32_e32 v12, v8, v9
	v_lshlrev_b32_e32 v8, 16, v240
	v_and_b32_e32 v9, 0xffff0000, v240
	v_lshlrev_b32_e32 v10, 16, v241
	v_and_b32_e32 v11, 0xffff0000, v241
	v_pk_fma_f32 v[6:7], v[6:7], 0.5, v[10:11] op_sel_hi:[1,0,1]
	v_pk_fma_f32 v[4:5], v[4:5], 0.5, v[8:9] op_sel_hi:[1,0,1]
	v_lshlrev_b32_e32 v8, 16, v242
	v_and_b32_e32 v9, 0xffff0000, v242
	v_lshlrev_b32_e32 v10, 16, v243
	v_and_b32_e32 v11, 0xffff0000, v243
	v_pk_fma_f32 v[10:11], v[2:3], 0.5, v[10:11] op_sel_hi:[1,0,1]
	v_pk_fma_f32 v[2:3], v[0:1], 0.5, v[8:9] op_sel_hi:[1,0,1]
	v_mul_f32_e32 v1, v5, v5
	v_cvt_pk_bf16_f32 v0, v4, v5
	v_fmac_f32_e32 v1, v4, v4
	v_mul_f32_e32 v4, v7, v7
	v_fmac_f32_e32 v4, v6, v6
	v_add_f32_e32 v1, v1, v4
	v_mul_f32_e32 v4, v3, v3
	v_mul_f32_e32 v5, v11, v11
	v_fmac_f32_e32 v4, v2, v2
	v_fmac_f32_e32 v5, v10, v10
	v_add_f32_e32 v4, v4, v5
	v_add_f32_e32 v1, v1, v4
	v_add_f32_e32 v4, v12, v1
	ds_bpermute_b32 v5, v114, v4
	v_cvt_pk_bf16_f32 v1, v6, v7
	v_cvt_pk_bf16_f32 v2, v2, v3
	v_cvt_pk_bf16_f32 v3, v10, v11
	global_store_dwordx4 v[94:95], v[0:3], off
	s_nop 1
	s_waitcnt lgkmcnt(0)
	v_add_f32_e32 v0, v4, v5
	v_mov_b32_e32 v1, v0
	s_nop 1
	v_permlane32_swap_b32_e32 v0, v1
	s_and_saveexec_b64 s[48:49], s[38:39]
	s_cbranch_execz .LBB0_1997
	v_add_u32_e32 v48, 0xb0, v168
	v_lshl_add_u64 v[2:3], v[48:49], 2, s[22:23]
	v_add_f32_e32 v0, v0, v1
	global_store_dword v[2:3], v0, off
